# attention half-wave exchanges (running max per key tile, final row sum) via v_permlane32_swap instead of ds_bpermute round trips
# speedup vs baseline: 1.0069x; 1.0069x over previous
.LBB0_103:
	ds_read_b128 v[2:5], v123
	ds_read_b128 v[6:9], v123 offset:32
	s_waitcnt lgkmcnt(1)
	v_mfma_f32_32x32x16_bf16 v[64:79], v[2:5], v[80:83], 0
	ds_read_b128 v[2:5], v123 offset:64
	s_waitcnt lgkmcnt(1)
	v_mfma_f32_32x32x16_bf16 v[64:79], v[6:9], v[84:87], v[64:79]
	s_waitcnt lgkmcnt(0)
	v_mfma_f32_32x32x16_bf16 v[64:79], v[2:5], v[88:91], v[64:79]
	ds_read_b128 v[2:5], v123 offset:96
	s_waitcnt lgkmcnt(0)
	v_mfma_f32_32x32x16_bf16 v[64:79], v[2:5], v[92:95], v[64:79]
	ds_read_b128 v[2:5], v123 offset:4608
	s_waitcnt lgkmcnt(0)
	v_mfma_f32_32x32x16_bf16 v[48:63], v[2:5], v[80:83], 0
	ds_read_b128 v[2:5], v123 offset:4640
	s_nop 7
	v_mul_f32_e32 v132, 0x3e38aa3b, v64
	v_mul_f32_e32 v131, 0x3e38aa3b, v65
	v_mul_f32_e32 v130, 0x3e38aa3b, v66
	v_mul_f32_e32 v129, 0x3e38aa3b, v67
	v_mul_f32_e32 v128, 0x3e38aa3b, v68
	v_mul_f32_e32 v127, 0x3e38aa3b, v69
	s_waitcnt lgkmcnt(0)
	v_mfma_f32_32x32x16_bf16 v[48:63], v[2:5], v[84:87], v[48:63]
	ds_read_b128 v[2:5], v123 offset:4672
	v_mul_f32_e32 v126, 0x3e38aa3b, v70
	v_mul_f32_e32 v71, 0x3e38aa3b, v71
	v_mul_f32_e32 v70, 0x3e38aa3b, v72
	v_mul_f32_e32 v69, 0x3e38aa3b, v73
	v_mul_f32_e32 v68, 0x3e38aa3b, v74
	v_mul_f32_e32 v67, 0x3e38aa3b, v75
	s_waitcnt lgkmcnt(0)
	v_mfma_f32_32x32x16_bf16 v[48:63], v[2:5], v[88:91], v[48:63]
	ds_read_b128 v[2:5], v123 offset:4704
	v_mul_f32_e32 v66, 0x3e38aa3b, v76
	v_mul_f32_e32 v65, 0x3e38aa3b, v77
	v_mul_f32_e32 v64, 0x3e38aa3b, v78
	s_waitcnt lgkmcnt(0)
	v_mfma_f32_32x32x16_bf16 v[48:63], v[2:5], v[92:95], v[48:63]
	v_max3_f32 v2, v132, s20, v131
	v_max3_f32 v2, v2, v130, v129
	v_max3_f32 v2, v2, v128, v127
	v_max3_f32 v2, v2, v126, v71
	v_max3_f32 v2, v2, v70, v69
	v_max3_f32 v2, v2, v68, v67
	v_mul_f32_e32 v4, 0x3e38aa3b, v79
	v_max3_f32 v2, v2, v66, v65
	s_nop 3
	v_mul_f32_e32 v5, 0x3e38aa3b, v48
	v_mul_f32_e32 v6, 0x3e38aa3b, v49
	v_max3_f32 v2, v2, v64, v4
	v_mul_f32_e32 v7, 0x3e38aa3b, v50
	v_mul_f32_e32 v8, 0x3e38aa3b, v51
	v_max3_f32 v2, v2, v5, v6
	v_mul_f32_e32 v9, 0x3e38aa3b, v52
	v_mul_f32_e32 v10, 0x3e38aa3b, v53
	v_max3_f32 v2, v2, v7, v8
	v_mul_f32_e32 v11, 0x3e38aa3b, v54
	v_mul_f32_e32 v12, 0x3e38aa3b, v55
	v_max3_f32 v2, v2, v9, v10
	v_mul_f32_e32 v13, 0x3e38aa3b, v56
	v_mul_f32_e32 v14, 0x3e38aa3b, v57
	v_max3_f32 v2, v2, v11, v12
	v_mul_f32_e32 v15, 0x3e38aa3b, v58
	v_mul_f32_e32 v48, 0x3e38aa3b, v59
	v_max3_f32 v2, v2, v13, v14
	v_mul_f32_e32 v49, 0x3e38aa3b, v60
	v_mul_f32_e32 v50, 0x3e38aa3b, v61
	v_max3_f32 v2, v2, v15, v48
	v_mul_f32_e32 v51, 0x3e38aa3b, v62
	v_mul_f32_e32 v52, 0x3e38aa3b, v63
	v_max3_f32 v2, v2, v49, v50
	v_max3_f32 v3, v2, v51, v52
	s_nop 1
	v_mov_b32_e32 v53, v3
	v_mov_b32_e32 v2, v3
	s_nop 1
	v_permlane32_swap_b32_e32 v53, v2
	v_max3_f32 v3, v125, v53, v2
	v_cmp_gt_f32_e32 vcc, v3, v125
	s_cbranch_vccz .LBB0_105
	v_sub_f32_e32 v53, v125, v3
	v_exp_f32_e32 v54, v53
	s_nop 0
	v_pk_mul_f32 v[46:47], v[46:47], v[54:55] op_sel_hi:[1,0]
	v_pk_mul_f32 v[44:45], v[44:45], v[54:55] op_sel_hi:[1,0]
	v_pk_mul_f32 v[42:43], v[42:43], v[54:55] op_sel_hi:[1,0]
	v_pk_mul_f32 v[40:41], v[40:41], v[54:55] op_sel_hi:[1,0]
	v_pk_mul_f32 v[38:39], v[38:39], v[54:55] op_sel_hi:[1,0]
	v_pk_mul_f32 v[36:37], v[36:37], v[54:55] op_sel_hi:[1,0]
	v_pk_mul_f32 v[34:35], v[34:35], v[54:55] op_sel_hi:[1,0]
	v_pk_mul_f32 v[32:33], v[32:33], v[54:55] op_sel_hi:[1,0]
	v_pk_mul_f32 v[30:31], v[30:31], v[54:55] op_sel_hi:[1,0]
	v_pk_mul_f32 v[28:29], v[28:29], v[54:55] op_sel_hi:[1,0]
	v_pk_mul_f32 v[26:27], v[26:27], v[54:55] op_sel_hi:[1,0]
	v_pk_mul_f32 v[24:25], v[24:25], v[54:55] op_sel_hi:[1,0]
	v_pk_mul_f32 v[22:23], v[22:23], v[54:55] op_sel_hi:[1,0]
	v_pk_mul_f32 v[20:21], v[20:21], v[54:55] op_sel_hi:[1,0]
	v_pk_mul_f32 v[18:19], v[18:19], v[54:55] op_sel_hi:[1,0]
	v_pk_mul_f32 v[16:17], v[16:17], v[54:55] op_sel_hi:[1,0]
	v_mul_f32_e32 v1, v1, v54

.LBB0_107:
	v_mov_b32_e32 v2, v1
	v_mov_b32_e32 v3, v1
	s_nop 1
	v_permlane32_swap_b32_e32 v2, v3
	v_readlane_b32 s64, v247, 53
	v_readlane_b32 s72, v247, 61
	v_readlane_b32 s65, v247, 54
	v_readlane_b32 s66, v247, 55
	s_waitcnt lgkmcnt(0)
	v_add_f32_e32 v1, v2, v3
	v_div_scale_f32 v2, s[0:1], v1, v1, 1.0
	v_rcp_f32_e32 v3, v2
	v_readlane_b32 s67, v247, 56
	v_readlane_b32 s68, v247, 57
	v_readlane_b32 s69, v247, 58
	v_fma_f32 v4, -v2, v3, 1.0
	v_fmac_f32_e32 v3, v4, v3
	v_div_scale_f32 v4, vcc, 1.0, v1, 1.0
	v_mul_f32_e32 v5, v4, v3
	v_fma_f32 v6, -v2, v5, v4
	v_fmac_f32_e32 v5, v6, v3
	v_fma_f32 v2, -v2, v5, v4
	v_div_fmas_f32 v2, v2, v3, v5
	v_lshlrev_b32_e32 v4, 1, v120
	v_mov_b32_e32 v5, v0
	v_lshl_add_u64 v[4:5], v[112:113], 0, v[4:5]
	global_load_dwordx2 v[6:7], v[4:5], off offset:1536
	global_load_dwordx2 v[154:155], v[4:5], off offset:1552
	global_load_dwordx2 v[156:157], v[4:5], off offset:1568
	global_load_dwordx2 v[158:159], v[4:5], off offset:1584
	global_load_dwordx2 v[160:161], v[4:5], off offset:1600
	global_load_dwordx2 v[162:163], v[4:5], off offset:1616
	global_load_dwordx2 v[164:165], v[4:5], off offset:1632
	global_load_dwordx2 v[166:167], v[4:5], off offset:1648
	v_div_fixup_f32 v2, v2, v1, 1.0
	v_pk_mul_f32 v[12:13], v[32:33], v[2:3] op_sel_hi:[1,0]
	v_readlane_b32 s70, v247, 59
	v_readlane_b32 s71, v247, 60
	v_readlane_b32 s74, v247, 63
	v_readlane_b32 s75, v246, 0
	v_readlane_b32 s76, v246, 1
	v_readlane_b32 s77, v246, 2
	v_readlane_b32 s78, v246, 3
	v_readlane_b32 s79, v246, 4
	v_readlane_b32 s72, v246, 60
	v_readlane_b32 s73, v247, 62
	s_waitcnt vmcnt(0)
	v_lshlrev_b32_e32 v8, 16, v6
	v_mul_f32_e32 v1, 0xbfb8aa3b, v8
	v_exp_f32_e32 v1, v1
	v_and_b32_e32 v9, 0xffff0000, v6
	v_add_f32_e32 v1, 1.0, v1
	v_rcp_f32_e32 v10, v1
	v_mul_f32_e32 v1, 0xbfb8aa3b, v9
	v_exp_f32_e32 v1, v1
	s_nop 0
	v_add_f32_e32 v1, 1.0, v1
	v_rcp_f32_e32 v11, v1
	s_nop 0
	v_pk_mul_f32 v[8:9], v[10:11], v[8:9]
	s_nop 0
	v_pk_mul_f32 v[8:9], v[12:13], v[8:9]
	v_pk_mul_f32 v[12:13], v[34:35], v[2:3] op_sel_hi:[1,0]
	v_cvt_pk_bf16_f32 v6, v8, v9
	v_lshlrev_b32_e32 v8, 16, v7
	v_mul_f32_e32 v1, 0xbfb8aa3b, v8
	v_exp_f32_e32 v1, v1
	v_and_b32_e32 v9, 0xffff0000, v7
	v_add_f32_e32 v1, 1.0, v1
	v_rcp_f32_e32 v10, v1
	v_mul_f32_e32 v1, 0xbfb8aa3b, v9
	v_exp_f32_e32 v1, v1
	s_nop 0
	v_add_f32_e32 v1, 1.0, v1
	v_rcp_f32_e32 v11, v1
	s_nop 0
	v_pk_mul_f32 v[8:9], v[10:11], v[8:9]
	s_nop 0
	v_pk_mul_f32 v[8:9], v[12:13], v[8:9]
	v_pk_mul_f32 v[12:13], v[36:37], v[2:3] op_sel_hi:[1,0]
	v_cvt_pk_bf16_f32 v7, v8, v9
	global_store_dwordx2 v[4:5], v[6:7], off
	v_mov_b32_e32 v6, v154
	v_mov_b32_e32 v7, v155
	v_lshlrev_b32_e32 v8, 16, v6
	v_mul_f32_e32 v1, 0xbfb8aa3b, v8
	v_exp_f32_e32 v1, v1
	v_and_b32_e32 v9, 0xffff0000, v6
	v_add_f32_e32 v1, 1.0, v1
	v_rcp_f32_e32 v10, v1
	v_mul_f32_e32 v1, 0xbfb8aa3b, v9
	v_exp_f32_e32 v1, v1
	s_nop 0
	v_add_f32_e32 v1, 1.0, v1
	v_rcp_f32_e32 v11, v1
	s_nop 0
	v_pk_mul_f32 v[8:9], v[10:11], v[8:9]
	s_nop 0
	v_pk_mul_f32 v[8:9], v[12:13], v[8:9]
	v_pk_mul_f32 v[12:13], v[38:39], v[2:3] op_sel_hi:[1,0]
	v_cvt_pk_bf16_f32 v6, v8, v9
	v_lshlrev_b32_e32 v8, 16, v7
	v_mul_f32_e32 v1, 0xbfb8aa3b, v8
	v_exp_f32_e32 v1, v1
	v_and_b32_e32 v9, 0xffff0000, v7
	v_add_f32_e32 v1, 1.0, v1
	v_rcp_f32_e32 v10, v1
	v_mul_f32_e32 v1, 0xbfb8aa3b, v9
	v_exp_f32_e32 v1, v1
	s_nop 0
	v_add_f32_e32 v1, 1.0, v1
	v_rcp_f32_e32 v11, v1
	s_nop 0
	v_pk_mul_f32 v[8:9], v[10:11], v[8:9]
	s_nop 0
	v_pk_mul_f32 v[8:9], v[12:13], v[8:9]
	v_pk_mul_f32 v[12:13], v[40:41], v[2:3] op_sel_hi:[1,0]
	v_cvt_pk_bf16_f32 v7, v8, v9
	global_store_dwordx2 v[4:5], v[6:7], off offset:16
	v_mov_b32_e32 v6, v156
	v_mov_b32_e32 v7, v157
	v_lshlrev_b32_e32 v8, 16, v6
	v_mul_f32_e32 v1, 0xbfb8aa3b, v8
	v_exp_f32_e32 v1, v1
	v_and_b32_e32 v9, 0xffff0000, v6
	v_add_f32_e32 v1, 1.0, v1
	v_rcp_f32_e32 v10, v1
	v_mul_f32_e32 v1, 0xbfb8aa3b, v9
	v_exp_f32_e32 v1, v1
	s_nop 0
	v_add_f32_e32 v1, 1.0, v1
	v_rcp_f32_e32 v11, v1
	s_nop 0
	v_pk_mul_f32 v[8:9], v[10:11], v[8:9]
	s_nop 0
	v_pk_mul_f32 v[8:9], v[12:13], v[8:9]
	v_pk_mul_f32 v[12:13], v[42:43], v[2:3] op_sel_hi:[1,0]
	v_cvt_pk_bf16_f32 v6, v8, v9
	v_lshlrev_b32_e32 v8, 16, v7
	v_mul_f32_e32 v1, 0xbfb8aa3b, v8
	v_exp_f32_e32 v1, v1
	v_and_b32_e32 v9, 0xffff0000, v7
	v_add_f32_e32 v1, 1.0, v1
	v_rcp_f32_e32 v10, v1
	v_mul_f32_e32 v1, 0xbfb8aa3b, v9
	v_exp_f32_e32 v1, v1
	s_nop 0
	v_add_f32_e32 v1, 1.0, v1
	v_rcp_f32_e32 v11, v1
	s_nop 0
	v_pk_mul_f32 v[8:9], v[10:11], v[8:9]
	s_nop 0
	v_pk_mul_f32 v[8:9], v[12:13], v[8:9]
	v_pk_mul_f32 v[12:13], v[44:45], v[2:3] op_sel_hi:[1,0]
	v_cvt_pk_bf16_f32 v7, v8, v9
	global_store_dwordx2 v[4:5], v[6:7], off offset:32
	v_mov_b32_e32 v6, v158
	v_mov_b32_e32 v7, v159
	v_lshlrev_b32_e32 v8, 16, v6
	v_mul_f32_e32 v1, 0xbfb8aa3b, v8
	v_exp_f32_e32 v1, v1
	v_and_b32_e32 v9, 0xffff0000, v6
	v_add_f32_e32 v1, 1.0, v1
	v_rcp_f32_e32 v10, v1
	v_mul_f32_e32 v1, 0xbfb8aa3b, v9
	v_exp_f32_e32 v1, v1
	s_nop 0
	v_add_f32_e32 v1, 1.0, v1
	v_rcp_f32_e32 v11, v1
	s_nop 0
	v_pk_mul_f32 v[8:9], v[10:11], v[8:9]
	s_nop 0
	v_pk_mul_f32 v[8:9], v[12:13], v[8:9]
	v_pk_mul_f32 v[12:13], v[46:47], v[2:3] op_sel_hi:[1,0]
	v_cvt_pk_bf16_f32 v6, v8, v9
	v_lshlrev_b32_e32 v8, 16, v7
	v_mul_f32_e32 v1, 0xbfb8aa3b, v8
	v_exp_f32_e32 v1, v1
	v_and_b32_e32 v9, 0xffff0000, v7
	v_add_f32_e32 v1, 1.0, v1
	v_rcp_f32_e32 v10, v1
	v_mul_f32_e32 v1, 0xbfb8aa3b, v9
	v_exp_f32_e32 v1, v1
	s_nop 0
	v_add_f32_e32 v1, 1.0, v1
	v_rcp_f32_e32 v11, v1
	s_nop 0
	v_pk_mul_f32 v[8:9], v[10:11], v[8:9]
	s_nop 0
	v_pk_mul_f32 v[8:9], v[12:13], v[8:9]
	v_pk_mul_f32 v[12:13], v[16:17], v[2:3] op_sel_hi:[1,0]
	v_cvt_pk_bf16_f32 v7, v8, v9
	global_store_dwordx2 v[4:5], v[6:7], off offset:48
	v_mov_b32_e32 v6, v160
	v_mov_b32_e32 v7, v161
	v_lshlrev_b32_e32 v8, 16, v6
	v_mul_f32_e32 v1, 0xbfb8aa3b, v8
	v_exp_f32_e32 v1, v1
	v_and_b32_e32 v9, 0xffff0000, v6
	v_add_f32_e32 v1, 1.0, v1
	v_rcp_f32_e32 v10, v1
	v_mul_f32_e32 v1, 0xbfb8aa3b, v9
	v_exp_f32_e32 v1, v1
	s_nop 0
	v_add_f32_e32 v1, 1.0, v1
	v_rcp_f32_e32 v11, v1
	s_nop 0
	v_pk_mul_f32 v[8:9], v[10:11], v[8:9]
	s_nop 0
	v_pk_mul_f32 v[8:9], v[12:13], v[8:9]
	v_pk_mul_f32 v[12:13], v[18:19], v[2:3] op_sel_hi:[1,0]
	v_cvt_pk_bf16_f32 v6, v8, v9
	v_lshlrev_b32_e32 v8, 16, v7
	v_mul_f32_e32 v1, 0xbfb8aa3b, v8
	v_exp_f32_e32 v1, v1
	v_and_b32_e32 v9, 0xffff0000, v7
	v_add_f32_e32 v1, 1.0, v1
	v_rcp_f32_e32 v10, v1
	v_mul_f32_e32 v1, 0xbfb8aa3b, v9
	v_exp_f32_e32 v1, v1
	s_nop 0
	v_add_f32_e32 v1, 1.0, v1
	v_rcp_f32_e32 v11, v1
	s_nop 0
	v_pk_mul_f32 v[8:9], v[10:11], v[8:9]
	s_nop 0
	v_pk_mul_f32 v[8:9], v[12:13], v[8:9]
	v_pk_mul_f32 v[12:13], v[20:21], v[2:3] op_sel_hi:[1,0]
	v_cvt_pk_bf16_f32 v7, v8, v9
	global_store_dwordx2 v[4:5], v[6:7], off offset:64
	v_mov_b32_e32 v6, v162
	v_mov_b32_e32 v7, v163
	v_lshlrev_b32_e32 v8, 16, v6
	v_mul_f32_e32 v1, 0xbfb8aa3b, v8
	v_exp_f32_e32 v1, v1
	v_and_b32_e32 v9, 0xffff0000, v6
	v_add_f32_e32 v1, 1.0, v1
	v_rcp_f32_e32 v10, v1
	v_mul_f32_e32 v1, 0xbfb8aa3b, v9
	v_exp_f32_e32 v1, v1
	s_nop 0
	v_add_f32_e32 v1, 1.0, v1
	v_rcp_f32_e32 v11, v1
	s_nop 0
	v_pk_mul_f32 v[8:9], v[10:11], v[8:9]
	s_nop 0
	v_pk_mul_f32 v[8:9], v[12:13], v[8:9]
	v_pk_mul_f32 v[12:13], v[22:23], v[2:3] op_sel_hi:[1,0]
	v_cvt_pk_bf16_f32 v6, v8, v9
	v_lshlrev_b32_e32 v8, 16, v7
	v_mul_f32_e32 v1, 0xbfb8aa3b, v8
	v_exp_f32_e32 v1, v1
	v_and_b32_e32 v9, 0xffff0000, v7
	v_add_f32_e32 v1, 1.0, v1
	v_rcp_f32_e32 v10, v1
	v_mul_f32_e32 v1, 0xbfb8aa3b, v9
	v_exp_f32_e32 v1, v1
	s_nop 0
	v_add_f32_e32 v1, 1.0, v1
	v_rcp_f32_e32 v11, v1
	s_nop 0
	v_pk_mul_f32 v[8:9], v[10:11], v[8:9]
	s_nop 0
	v_pk_mul_f32 v[8:9], v[12:13], v[8:9]
	v_pk_mul_f32 v[12:13], v[24:25], v[2:3] op_sel_hi:[1,0]
	v_cvt_pk_bf16_f32 v7, v8, v9
	global_store_dwordx2 v[4:5], v[6:7], off offset:80
	v_mov_b32_e32 v6, v164
	v_mov_b32_e32 v7, v165
	v_lshlrev_b32_e32 v8, 16, v6
	v_mul_f32_e32 v1, 0xbfb8aa3b, v8
	v_exp_f32_e32 v1, v1
	v_and_b32_e32 v9, 0xffff0000, v6
	v_add_f32_e32 v1, 1.0, v1
	v_rcp_f32_e32 v10, v1
	v_mul_f32_e32 v1, 0xbfb8aa3b, v9
	v_exp_f32_e32 v1, v1
	s_nop 0
	v_add_f32_e32 v1, 1.0, v1
	v_rcp_f32_e32 v11, v1
	s_nop 0
	v_pk_mul_f32 v[8:9], v[10:11], v[8:9]
	s_nop 0
	v_pk_mul_f32 v[8:9], v[12:13], v[8:9]
	v_pk_mul_f32 v[12:13], v[26:27], v[2:3] op_sel_hi:[1,0]
	v_cvt_pk_bf16_f32 v6, v8, v9
	v_lshlrev_b32_e32 v8, 16, v7
	v_mul_f32_e32 v1, 0xbfb8aa3b, v8
	v_exp_f32_e32 v1, v1
	v_and_b32_e32 v9, 0xffff0000, v7
	v_add_f32_e32 v1, 1.0, v1
	v_rcp_f32_e32 v10, v1
	v_mul_f32_e32 v1, 0xbfb8aa3b, v9
	v_exp_f32_e32 v1, v1
	s_nop 0
	v_add_f32_e32 v1, 1.0, v1
	v_rcp_f32_e32 v11, v1
	s_nop 0
	v_pk_mul_f32 v[8:9], v[10:11], v[8:9]
	s_nop 0
	v_pk_mul_f32 v[8:9], v[12:13], v[8:9]
	v_pk_mul_f32 v[12:13], v[28:29], v[2:3] op_sel_hi:[1,0]
	v_cvt_pk_bf16_f32 v7, v8, v9
	global_store_dwordx2 v[4:5], v[6:7], off offset:96
	v_mov_b32_e32 v6, v166
	v_mov_b32_e32 v7, v167
	v_pk_mul_f32 v[2:3], v[30:31], v[2:3] op_sel_hi:[1,0]
	v_lshlrev_b32_e32 v8, 16, v6
	v_mul_f32_e32 v1, 0xbfb8aa3b, v8
	v_exp_f32_e32 v1, v1
	v_and_b32_e32 v9, 0xffff0000, v6
	v_add_f32_e32 v1, 1.0, v1
	v_rcp_f32_e32 v10, v1
	v_mul_f32_e32 v1, 0xbfb8aa3b, v9
	v_exp_f32_e32 v1, v1
	s_nop 0
	v_add_f32_e32 v1, 1.0, v1
	v_rcp_f32_e32 v11, v1
	s_nop 0
	v_pk_mul_f32 v[8:9], v[10:11], v[8:9]
	s_nop 0
	v_pk_mul_f32 v[8:9], v[12:13], v[8:9]
	s_nop 0
	v_cvt_pk_bf16_f32 v6, v8, v9
	v_lshlrev_b32_e32 v8, 16, v7
	v_mul_f32_e32 v1, 0xbfb8aa3b, v8
	v_exp_f32_e32 v1, v1
	v_and_b32_e32 v9, 0xffff0000, v7
	v_add_f32_e32 v1, 1.0, v1
	v_rcp_f32_e32 v10, v1
	v_mul_f32_e32 v1, 0xbfb8aa3b, v9
	v_exp_f32_e32 v1, v1
	s_nop 0
	v_add_f32_e32 v1, 1.0, v1
	v_rcp_f32_e32 v11, v1
	s_nop 0
	v_pk_mul_f32 v[8:9], v[10:11], v[8:9]
	s_nop 0
	v_pk_mul_f32 v[2:3], v[2:3], v[8:9]
	s_nop 0
	v_cvt_pk_bf16_f32 v7, v2, v3
	global_store_dwordx2 v[4:5], v[6:7], off offset:112

.LBB0_138:
	s_or_b64 exec, exec, s[40:41]
	s_nop 5
	v_mov_b32_e32 v48, v1
	v_mov_b32_e32 v49, v1
	s_nop 1
	v_permlane32_swap_b32_e32 v48, v49
	v_max3_f32 v1, v244, v48, v49
	v_cmp_gt_f32_e32 vcc, v1, v244
	s_cbranch_vccz .LBB0_140
	v_sub_f32_e32 v48, v244, v1
	v_exp_f32_e32 v48, v48
	s_nop 0
	v_pk_mul_f32 v[46:47], v[46:47], v[48:49] op_sel_hi:[1,0]
	v_pk_mul_f32 v[44:45], v[44:45], v[48:49] op_sel_hi:[1,0]
	v_pk_mul_f32 v[42:43], v[42:43], v[48:49] op_sel_hi:[1,0]
	v_pk_mul_f32 v[40:41], v[40:41], v[48:49] op_sel_hi:[1,0]
	v_pk_mul_f32 v[38:39], v[38:39], v[48:49] op_sel_hi:[1,0]
	v_pk_mul_f32 v[36:37], v[36:37], v[48:49] op_sel_hi:[1,0]
	v_pk_mul_f32 v[34:35], v[34:35], v[48:49] op_sel_hi:[1,0]
	v_pk_mul_f32 v[32:33], v[32:33], v[48:49] op_sel_hi:[1,0]
	v_pk_mul_f32 v[30:31], v[30:31], v[48:49] op_sel_hi:[1,0]
	v_pk_mul_f32 v[28:29], v[28:29], v[48:49] op_sel_hi:[1,0]
	v_pk_mul_f32 v[26:27], v[26:27], v[48:49] op_sel_hi:[1,0]
	v_pk_mul_f32 v[24:25], v[24:25], v[48:49] op_sel_hi:[1,0]
	v_pk_mul_f32 v[22:23], v[22:23], v[48:49] op_sel_hi:[1,0]
	v_pk_mul_f32 v[20:21], v[20:21], v[48:49] op_sel_hi:[1,0]
	v_pk_mul_f32 v[18:19], v[18:19], v[48:49] op_sel_hi:[1,0]
	v_pk_mul_f32 v[16:17], v[16:17], v[48:49] op_sel_hi:[1,0]
	v_mul_f32_e32 v243, v243, v48

.LBB0_143:
	v_mov_b32_e32 v1, v243
	v_mov_b32_e32 v2, v243
	v_readlane_b32 s64, v247, 53
	v_readlane_b32 s72, v247, 61
	v_permlane32_swap_b32_e32 v1, v2
	v_readlane_b32 s65, v247, 54
	v_readlane_b32 s66, v247, 55
	v_readlane_b32 s67, v247, 56
	v_readlane_b32 s68, v247, 57
	s_waitcnt lgkmcnt(0)
	v_add_f32_e32 v1, v1, v2
	v_div_scale_f32 v2, s[0:1], v1, v1, 1.0
	v_rcp_f32_e32 v3, v2
	v_readlane_b32 s69, v247, 58
	v_readlane_b32 s70, v247, 59
	v_readlane_b32 s71, v247, 60
	v_fma_f32 v4, -v2, v3, 1.0
	v_fmac_f32_e32 v3, v4, v3
	v_div_scale_f32 v4, vcc, 1.0, v1, 1.0
	v_mul_f32_e32 v5, v4, v3
	v_fma_f32 v6, -v2, v5, v4
	v_fmac_f32_e32 v5, v6, v3
	v_fma_f32 v2, -v2, v5, v4
	v_div_fmas_f32 v2, v2, v3, v5
	v_lshlrev_b32_e32 v4, 1, v151
	v_mov_b32_e32 v5, v0
	v_lshl_add_u64 v[4:5], v[152:153], 0, v[4:5]
	global_load_dwordx2 v[6:7], v[4:5], off offset:1536
	global_load_dwordx2 v[154:155], v[4:5], off offset:1552
	global_load_dwordx2 v[156:157], v[4:5], off offset:1568
	global_load_dwordx2 v[158:159], v[4:5], off offset:1584
	global_load_dwordx2 v[160:161], v[4:5], off offset:1600
	global_load_dwordx2 v[162:163], v[4:5], off offset:1616
	global_load_dwordx2 v[164:165], v[4:5], off offset:1632
	global_load_dwordx2 v[166:167], v[4:5], off offset:1648
	v_div_fixup_f32 v2, v2, v1, 1.0
	v_pk_mul_f32 v[12:13], v[32:33], v[2:3] op_sel_hi:[1,0]
	v_readlane_b32 s74, v247, 63
	v_readlane_b32 s75, v246, 0
	v_readlane_b32 s76, v246, 1
	v_readlane_b32 s77, v246, 2
	v_readlane_b32 s78, v246, 3
	v_readlane_b32 s79, v246, 4
	v_readlane_b32 s72, v246, 60
	v_readlane_b32 s73, v247, 62
	s_waitcnt vmcnt(0)
	v_lshlrev_b32_e32 v8, 16, v6
	v_mul_f32_e32 v1, 0xbfb8aa3b, v8
	v_exp_f32_e32 v1, v1
	v_and_b32_e32 v9, 0xffff0000, v6
	v_add_f32_e32 v1, 1.0, v1
	v_rcp_f32_e32 v10, v1
	v_mul_f32_e32 v1, 0xbfb8aa3b, v9
	v_exp_f32_e32 v1, v1
	s_nop 0
	v_add_f32_e32 v1, 1.0, v1
	v_rcp_f32_e32 v11, v1
	s_nop 0
	v_pk_mul_f32 v[8:9], v[10:11], v[8:9]
	s_nop 0
	v_pk_mul_f32 v[8:9], v[12:13], v[8:9]
	v_pk_mul_f32 v[12:13], v[34:35], v[2:3] op_sel_hi:[1,0]
	v_cvt_pk_bf16_f32 v6, v8, v9
	v_lshlrev_b32_e32 v8, 16, v7
	v_mul_f32_e32 v1, 0xbfb8aa3b, v8
	v_exp_f32_e32 v1, v1
	v_and_b32_e32 v9, 0xffff0000, v7
	v_add_f32_e32 v1, 1.0, v1
	v_rcp_f32_e32 v10, v1
	v_mul_f32_e32 v1, 0xbfb8aa3b, v9
	v_exp_f32_e32 v1, v1
	s_nop 0
	v_add_f32_e32 v1, 1.0, v1
	v_rcp_f32_e32 v11, v1
	s_nop 0
	v_pk_mul_f32 v[8:9], v[10:11], v[8:9]
	s_nop 0
	v_pk_mul_f32 v[8:9], v[12:13], v[8:9]
	v_pk_mul_f32 v[12:13], v[36:37], v[2:3] op_sel_hi:[1,0]
	v_cvt_pk_bf16_f32 v7, v8, v9
	global_store_dwordx2 v[4:5], v[6:7], off
	v_mov_b32_e32 v6, v154
	v_mov_b32_e32 v7, v155
	v_lshlrev_b32_e32 v8, 16, v6
	v_mul_f32_e32 v1, 0xbfb8aa3b, v8
	v_exp_f32_e32 v1, v1
	v_and_b32_e32 v9, 0xffff0000, v6
	v_add_f32_e32 v1, 1.0, v1
	v_rcp_f32_e32 v10, v1
	v_mul_f32_e32 v1, 0xbfb8aa3b, v9
	v_exp_f32_e32 v1, v1
	s_nop 0
	v_add_f32_e32 v1, 1.0, v1
	v_rcp_f32_e32 v11, v1
	s_nop 0
	v_pk_mul_f32 v[8:9], v[10:11], v[8:9]
	s_nop 0
	v_pk_mul_f32 v[8:9], v[12:13], v[8:9]
	v_pk_mul_f32 v[12:13], v[38:39], v[2:3] op_sel_hi:[1,0]
	v_cvt_pk_bf16_f32 v6, v8, v9
	v_lshlrev_b32_e32 v8, 16, v7
	v_mul_f32_e32 v1, 0xbfb8aa3b, v8
	v_exp_f32_e32 v1, v1
	v_and_b32_e32 v9, 0xffff0000, v7
	v_add_f32_e32 v1, 1.0, v1
	v_rcp_f32_e32 v10, v1
	v_mul_f32_e32 v1, 0xbfb8aa3b, v9
	v_exp_f32_e32 v1, v1
	s_nop 0
	v_add_f32_e32 v1, 1.0, v1
	v_rcp_f32_e32 v11, v1
	s_nop 0
	v_pk_mul_f32 v[8:9], v[10:11], v[8:9]
	s_nop 0
	v_pk_mul_f32 v[8:9], v[12:13], v[8:9]
	v_pk_mul_f32 v[12:13], v[40:41], v[2:3] op_sel_hi:[1,0]
	v_cvt_pk_bf16_f32 v7, v8, v9
	global_store_dwordx2 v[4:5], v[6:7], off offset:16
	v_mov_b32_e32 v6, v156
	v_mov_b32_e32 v7, v157
	v_lshlrev_b32_e32 v8, 16, v6
	v_mul_f32_e32 v1, 0xbfb8aa3b, v8
	v_exp_f32_e32 v1, v1
	v_and_b32_e32 v9, 0xffff0000, v6
	v_add_f32_e32 v1, 1.0, v1
	v_rcp_f32_e32 v10, v1
	v_mul_f32_e32 v1, 0xbfb8aa3b, v9
	v_exp_f32_e32 v1, v1
	s_nop 0
	v_add_f32_e32 v1, 1.0, v1
	v_rcp_f32_e32 v11, v1
	s_nop 0
	v_pk_mul_f32 v[8:9], v[10:11], v[8:9]
	s_nop 0
	v_pk_mul_f32 v[8:9], v[12:13], v[8:9]
	v_pk_mul_f32 v[12:13], v[42:43], v[2:3] op_sel_hi:[1,0]
	v_cvt_pk_bf16_f32 v6, v8, v9
	v_lshlrev_b32_e32 v8, 16, v7
	v_mul_f32_e32 v1, 0xbfb8aa3b, v8
	v_exp_f32_e32 v1, v1
	v_and_b32_e32 v9, 0xffff0000, v7
	v_add_f32_e32 v1, 1.0, v1
	v_rcp_f32_e32 v10, v1
	v_mul_f32_e32 v1, 0xbfb8aa3b, v9
	v_exp_f32_e32 v1, v1
	s_nop 0
	v_add_f32_e32 v1, 1.0, v1
	v_rcp_f32_e32 v11, v1
	s_nop 0
	v_pk_mul_f32 v[8:9], v[10:11], v[8:9]
	s_nop 0
	v_pk_mul_f32 v[8:9], v[12:13], v[8:9]
	v_pk_mul_f32 v[12:13], v[44:45], v[2:3] op_sel_hi:[1,0]
	v_cvt_pk_bf16_f32 v7, v8, v9
	global_store_dwordx2 v[4:5], v[6:7], off offset:32
	v_mov_b32_e32 v6, v158
	v_mov_b32_e32 v7, v159
	v_lshlrev_b32_e32 v8, 16, v6
	v_mul_f32_e32 v1, 0xbfb8aa3b, v8
	v_exp_f32_e32 v1, v1
	v_and_b32_e32 v9, 0xffff0000, v6
	v_add_f32_e32 v1, 1.0, v1
	v_rcp_f32_e32 v10, v1
	v_mul_f32_e32 v1, 0xbfb8aa3b, v9
	v_exp_f32_e32 v1, v1
	s_nop 0
	v_add_f32_e32 v1, 1.0, v1
	v_rcp_f32_e32 v11, v1
	s_nop 0
	v_pk_mul_f32 v[8:9], v[10:11], v[8:9]
	s_nop 0
	v_pk_mul_f32 v[8:9], v[12:13], v[8:9]
	v_pk_mul_f32 v[12:13], v[46:47], v[2:3] op_sel_hi:[1,0]
	v_cvt_pk_bf16_f32 v6, v8, v9
	v_lshlrev_b32_e32 v8, 16, v7
	v_mul_f32_e32 v1, 0xbfb8aa3b, v8
	v_exp_f32_e32 v1, v1
	v_and_b32_e32 v9, 0xffff0000, v7
	v_add_f32_e32 v1, 1.0, v1
	v_rcp_f32_e32 v10, v1
	v_mul_f32_e32 v1, 0xbfb8aa3b, v9
	v_exp_f32_e32 v1, v1
	s_nop 0
	v_add_f32_e32 v1, 1.0, v1
	v_rcp_f32_e32 v11, v1
	s_nop 0
	v_pk_mul_f32 v[8:9], v[10:11], v[8:9]
	s_nop 0
	v_pk_mul_f32 v[8:9], v[12:13], v[8:9]
	v_pk_mul_f32 v[12:13], v[16:17], v[2:3] op_sel_hi:[1,0]
	v_cvt_pk_bf16_f32 v7, v8, v9
	global_store_dwordx2 v[4:5], v[6:7], off offset:48
	v_mov_b32_e32 v6, v160
	v_mov_b32_e32 v7, v161
	v_lshlrev_b32_e32 v8, 16, v6
	v_mul_f32_e32 v1, 0xbfb8aa3b, v8
	v_exp_f32_e32 v1, v1
	v_and_b32_e32 v9, 0xffff0000, v6
	v_add_f32_e32 v1, 1.0, v1
	v_rcp_f32_e32 v10, v1
	v_mul_f32_e32 v1, 0xbfb8aa3b, v9
	v_exp_f32_e32 v1, v1
	s_nop 0
	v_add_f32_e32 v1, 1.0, v1
	v_rcp_f32_e32 v11, v1
	s_nop 0
	v_pk_mul_f32 v[8:9], v[10:11], v[8:9]
	s_nop 0
	v_pk_mul_f32 v[8:9], v[12:13], v[8:9]
	v_pk_mul_f32 v[12:13], v[18:19], v[2:3] op_sel_hi:[1,0]
	v_cvt_pk_bf16_f32 v6, v8, v9
	v_lshlrev_b32_e32 v8, 16, v7
	v_mul_f32_e32 v1, 0xbfb8aa3b, v8
	v_exp_f32_e32 v1, v1
	v_and_b32_e32 v9, 0xffff0000, v7
	v_add_f32_e32 v1, 1.0, v1
	v_rcp_f32_e32 v10, v1
	v_mul_f32_e32 v1, 0xbfb8aa3b, v9
	v_exp_f32_e32 v1, v1
	s_nop 0
	v_add_f32_e32 v1, 1.0, v1
	v_rcp_f32_e32 v11, v1
	s_nop 0
	v_pk_mul_f32 v[8:9], v[10:11], v[8:9]
	s_nop 0
	v_pk_mul_f32 v[8:9], v[12:13], v[8:9]
	v_pk_mul_f32 v[12:13], v[20:21], v[2:3] op_sel_hi:[1,0]
	v_cvt_pk_bf16_f32 v7, v8, v9
	global_store_dwordx2 v[4:5], v[6:7], off offset:64
	v_mov_b32_e32 v6, v162
	v_mov_b32_e32 v7, v163
	v_lshlrev_b32_e32 v8, 16, v6
	v_mul_f32_e32 v1, 0xbfb8aa3b, v8
	v_exp_f32_e32 v1, v1
	v_and_b32_e32 v9, 0xffff0000, v6
	v_add_f32_e32 v1, 1.0, v1
	v_rcp_f32_e32 v10, v1
	v_mul_f32_e32 v1, 0xbfb8aa3b, v9
	v_exp_f32_e32 v1, v1
	s_nop 0
	v_add_f32_e32 v1, 1.0, v1
	v_rcp_f32_e32 v11, v1
	s_nop 0
	v_pk_mul_f32 v[8:9], v[10:11], v[8:9]
	s_nop 0
	v_pk_mul_f32 v[8:9], v[12:13], v[8:9]
	v_pk_mul_f32 v[12:13], v[22:23], v[2:3] op_sel_hi:[1,0]
	v_cvt_pk_bf16_f32 v6, v8, v9
	v_lshlrev_b32_e32 v8, 16, v7
	v_mul_f32_e32 v1, 0xbfb8aa3b, v8
	v_exp_f32_e32 v1, v1
	v_and_b32_e32 v9, 0xffff0000, v7
	v_add_f32_e32 v1, 1.0, v1
	v_rcp_f32_e32 v10, v1
	v_mul_f32_e32 v1, 0xbfb8aa3b, v9
	v_exp_f32_e32 v1, v1
	s_nop 0
	v_add_f32_e32 v1, 1.0, v1
	v_rcp_f32_e32 v11, v1
	s_nop 0
	v_pk_mul_f32 v[8:9], v[10:11], v[8:9]
	s_nop 0
	v_pk_mul_f32 v[8:9], v[12:13], v[8:9]
	v_pk_mul_f32 v[12:13], v[24:25], v[2:3] op_sel_hi:[1,0]
	v_cvt_pk_bf16_f32 v7, v8, v9
	global_store_dwordx2 v[4:5], v[6:7], off offset:80
	v_mov_b32_e32 v6, v164
	v_mov_b32_e32 v7, v165
	v_lshlrev_b32_e32 v8, 16, v6
	v_mul_f32_e32 v1, 0xbfb8aa3b, v8
	v_exp_f32_e32 v1, v1
	v_and_b32_e32 v9, 0xffff0000, v6
	v_add_f32_e32 v1, 1.0, v1
	v_rcp_f32_e32 v10, v1
	v_mul_f32_e32 v1, 0xbfb8aa3b, v9
	v_exp_f32_e32 v1, v1
	s_nop 0
	v_add_f32_e32 v1, 1.0, v1
	v_rcp_f32_e32 v11, v1
	s_nop 0
	v_pk_mul_f32 v[8:9], v[10:11], v[8:9]
	s_nop 0
	v_pk_mul_f32 v[8:9], v[12:13], v[8:9]
	v_pk_mul_f32 v[12:13], v[26:27], v[2:3] op_sel_hi:[1,0]
	v_cvt_pk_bf16_f32 v6, v8, v9
	v_lshlrev_b32_e32 v8, 16, v7
	v_mul_f32_e32 v1, 0xbfb8aa3b, v8
	v_exp_f32_e32 v1, v1
	v_and_b32_e32 v9, 0xffff0000, v7
	v_add_f32_e32 v1, 1.0, v1
	v_rcp_f32_e32 v10, v1
	v_mul_f32_e32 v1, 0xbfb8aa3b, v9
	v_exp_f32_e32 v1, v1
	s_nop 0
	v_add_f32_e32 v1, 1.0, v1
	v_rcp_f32_e32 v11, v1
	s_nop 0
	v_pk_mul_f32 v[8:9], v[10:11], v[8:9]
	s_nop 0
	v_pk_mul_f32 v[8:9], v[12:13], v[8:9]
	v_pk_mul_f32 v[12:13], v[28:29], v[2:3] op_sel_hi:[1,0]
	v_cvt_pk_bf16_f32 v7, v8, v9
	global_store_dwordx2 v[4:5], v[6:7], off offset:96
	v_mov_b32_e32 v6, v166
	v_mov_b32_e32 v7, v167
	v_pk_mul_f32 v[2:3], v[30:31], v[2:3] op_sel_hi:[1,0]
	v_lshlrev_b32_e32 v8, 16, v6
	v_mul_f32_e32 v1, 0xbfb8aa3b, v8
	v_exp_f32_e32 v1, v1
	v_and_b32_e32 v9, 0xffff0000, v6
	v_add_f32_e32 v1, 1.0, v1
	v_rcp_f32_e32 v10, v1
	v_mul_f32_e32 v1, 0xbfb8aa3b, v9
	v_exp_f32_e32 v1, v1
	s_nop 0
	v_add_f32_e32 v1, 1.0, v1
	v_rcp_f32_e32 v11, v1
	s_nop 0
	v_pk_mul_f32 v[8:9], v[10:11], v[8:9]
	s_nop 0
	v_pk_mul_f32 v[8:9], v[12:13], v[8:9]
	s_nop 0
	v_cvt_pk_bf16_f32 v6, v8, v9
	v_lshlrev_b32_e32 v8, 16, v7
	v_mul_f32_e32 v1, 0xbfb8aa3b, v8
	v_exp_f32_e32 v1, v1
	v_and_b32_e32 v9, 0xffff0000, v7
	v_add_f32_e32 v1, 1.0, v1
	v_rcp_f32_e32 v10, v1
	v_mul_f32_e32 v1, 0xbfb8aa3b, v9
	v_exp_f32_e32 v1, v1
	s_nop 0
	v_add_f32_e32 v1, 1.0, v1
	v_rcp_f32_e32 v11, v1
	s_nop 0
	v_pk_mul_f32 v[8:9], v[10:11], v[8:9]
	s_nop 0
	v_pk_mul_f32 v[2:3], v[2:3], v[8:9]
	s_nop 0
	v_cvt_pk_bf16_f32 v7, v2, v3
	global_store_dwordx2 v[4:5], v[6:7], off offset:112
